# P4 k_nope / v^T calls: the 14 filler DMA loads per wave of the single K-loop pass removed, waits re-counted
# baseline (speedup 1.0000x reference)
; #define PG8_STAGE(bufoff, gbase, voff) do { _Pragma("unroll") for (int _i = 0; _i < 2; ++_i) \
;         __builtin_amdgcn_global_load_lds((const unsigned*)((const char*)(gbase) + (voff)[_i]), (PG8_LAS unsigned*)(lds + (bufoff) + ldsw + _i * 8192), 16, 0, 0); } while (0)
; #define PG8_LDA(dst, b, h) do { _Pragma("unroll") for (int m = 0; m < 4; ++m) _Pragma("unroll") for (int k = 0; k < 2; ++k) dst[m][k] = *(const PG8_LAS bf16x8*)(lds + PG8_SA(b, h) + aoff + m * 2048 + k * 1024); } while (0)
; #define PG8_LDB(dst, b, h) do { _Pragma("unroll") for (int n = 0; n < 2; ++n) _Pragma("unroll") for (int k = 0; k < 2; ++k) dst[n][k] = *(const PG8_LAS bf16x8*)(lds + PG8_SB(b, h) + boff + n * 2048 + k * 1024); } while (0)
; #define PG8_WAIT_V(n) asm volatile("s_waitcnt vmcnt(" #n ")" ::: "memory")
; #define PG8_WAIT_L(n) asm volatile("s_waitcnt lgkmcnt(" #n ")" ::: "memory")
; #define PG8_BAR __builtin_amdgcn_s_barrier()
; #define PG8_SCHED __builtin_amdgcn_sched_barrier(0)
; template <class Epi, class Sched, bool ALIGN_EPI = false, bool SP2 = false>
; __device__ __forceinline__ void gemm_phase(PG8_LAS unsigned char* lds, const Gemm g, const Sched& S, const Epi& E) {
;     ...
;             PG8_LDB(B0, 0, 0); PG8_LDB(B1, 0, 1); PG8_SCHED; PG8_LDA(At, 0, 0); PG8_STAGE(PG8_SA(1, 1), a1 + hstep, voffA);
;             PG8_WAIT_V(8); PG8_WAIT_L(0); PG8_BAR; PG8_MMA(0, 0, At, B0); PG8_MMA(0, 1, At, B1); PG8_BAR; PG8_SCHED;
;             PG8_LDA(At, 0, 1); PG8_STAGE(PG8_SB(0, 0), b2, voffB); PG8_STAGE(PG8_SB(0, 1), b2 + hstep, voffB); PG8_STAGE(PG8_SA(0, 0), a2, voffA);
;             PG8_WAIT_V(8); PG8_WAIT_L(0); PG8_BAR; PG8_MMA(1, 0, At, B0); PG8_MMA(1, 1, At, B1); PG8_BAR; PG8_SCHED;
;             PG8_LDB(B0, 1, 0); PG8_LDB(B1, 1, 1); PG8_SCHED; PG8_LDA(At, 1, 0); PG8_STAGE(PG8_SA(0, 1), a2 + hstep, voffA);
;             PG8_WAIT_V(8); PG8_WAIT_L(0); PG8_BAR; PG8_MMA(0, 0, At, B0); PG8_MMA(0, 1, At, B1); PG8_BAR; PG8_SCHED;
;             PG8_LDA(At, 1, 1); PG8_STAGE(PG8_SB(1, 0), b3, voffB); PG8_STAGE(PG8_SB(1, 1), b3 + hstep, voffB); PG8_STAGE(PG8_SA(1, 0), a3, voffA);
;             PG8_WAIT_V(8); PG8_WAIT_L(0); PG8_BAR; PG8_MMA(1, 0, At, B0); PG8_MMA(1, 1, At, B1); PG8_BAR; PG8_SCHED;
.LBB0_439:
	ds_read_b128 v[150:153], v147
	ds_read_b128 v[154:157], v147 offset:1024
	ds_read_b128 v[158:161], v147 offset:2048
	ds_read_b128 v[162:165], v147 offset:3072
	ds_read_b128 v[166:169], v148
	ds_read_b128 v[170:173], v148 offset:1024
	ds_read_b128 v[174:177], v148 offset:2048
	ds_read_b128 v[178:181], v148 offset:3072
	s_add_i32 s77, s56, 2
	s_add_u32 s26, s54, 0x80
	s_addc_u32 s27, s55, 0
	s_cmp_eq_u32 s65, s56
	s_cselect_b32 s56, s6, s26
	s_cselect_b32 s57, s7, s27
	s_cselect_b32 s79, s53, s76
	s_cselect_b32 s78, s52, s75
	v_lshl_add_u64 v[216:217], s[54:55], 0, v[136:137]
	s_add_i32 m0, s37, 0xc000
	ds_read_b128 v[182:185], v149
	ds_read_b128 v[186:189], v149 offset:1024
	ds_read_b128 v[190:193], v149 offset:2048
	ds_read_b128 v[196:199], v149 offset:3072
	ds_read_b128 v[200:203], v149 offset:4096
	ds_read_b128 v[204:207], v149 offset:5120
	ds_read_b128 v[208:211], v149 offset:6144
	ds_read_b128 v[212:215], v149 offset:7168
	global_load_lds_dwordx4 v[216:217], off
	v_lshl_add_u64 v[216:217], s[54:55], 0, v[138:139]
	s_add_i32 m0, s37, 0xe000
	s_nop 0
	global_load_lds_dwordx4 v[216:217], off
	s_waitcnt vmcnt(8)
	s_waitcnt lgkmcnt(0)
	s_barrier
	s_setprio 1
	s_waitcnt lgkmcnt(0)
	v_mfma_f32_16x16x32_bf16 v[120:123], v[150:153], v[182:185], v[120:123]
	v_mfma_f32_16x16x32_bf16 v[124:127], v[158:161], v[182:185], v[124:127]
	v_mfma_f32_16x16x32_bf16 v[108:111], v[150:153], v[190:193], v[108:111]
	v_mfma_f32_16x16x32_bf16 v[104:107], v[158:161], v[190:193], v[104:107]
	v_mfma_f32_16x16x32_bf16 v[92:95], v[150:153], v[200:203], v[92:95]
	v_mfma_f32_16x16x32_bf16 v[88:91], v[158:161], v[200:203], v[88:91]
	v_mfma_f32_16x16x32_bf16 v[76:79], v[150:153], v[208:211], v[76:79]
	v_mfma_f32_16x16x32_bf16 v[72:75], v[158:161], v[208:211], v[72:75]
	v_mfma_f32_16x16x32_bf16 v[120:123], v[154:157], v[186:189], v[120:123]
	v_mfma_f32_16x16x32_bf16 v[124:127], v[162:165], v[186:189], v[124:127]
	v_mfma_f32_16x16x32_bf16 v[108:111], v[154:157], v[196:199], v[108:111]
	v_mfma_f32_16x16x32_bf16 v[104:107], v[162:165], v[196:199], v[104:107]
	v_mfma_f32_16x16x32_bf16 v[92:95], v[154:157], v[204:207], v[92:95]
	v_mfma_f32_16x16x32_bf16 v[88:91], v[162:165], v[204:207], v[88:91]
	v_mfma_f32_16x16x32_bf16 v[76:79], v[154:157], v[212:215], v[76:79]
	v_mfma_f32_16x16x32_bf16 v[72:75], v[162:165], v[212:215], v[72:75]
	s_setprio 0
	s_setprio 1
	v_mfma_f32_16x16x32_bf16 v[116:119], v[166:169], v[182:185], v[116:119]
	v_mfma_f32_16x16x32_bf16 v[112:115], v[174:177], v[182:185], v[112:115]
	v_mfma_f32_16x16x32_bf16 v[100:103], v[166:169], v[190:193], v[100:103]
	v_mfma_f32_16x16x32_bf16 v[96:99], v[174:177], v[190:193], v[96:99]
	v_mfma_f32_16x16x32_bf16 v[84:87], v[166:169], v[200:203], v[84:87]
	v_mfma_f32_16x16x32_bf16 v[80:83], v[174:177], v[200:203], v[80:83]
	v_mfma_f32_16x16x32_bf16 v[68:71], v[166:169], v[208:211], v[68:71]
	v_mfma_f32_16x16x32_bf16 v[64:67], v[174:177], v[208:211], v[64:67]
	v_mfma_f32_16x16x32_bf16 v[116:119], v[170:173], v[186:189], v[116:119]
	v_mfma_f32_16x16x32_bf16 v[112:115], v[178:181], v[186:189], v[112:115]
	v_mfma_f32_16x16x32_bf16 v[100:103], v[170:173], v[196:199], v[100:103]
	v_mfma_f32_16x16x32_bf16 v[96:99], v[178:181], v[196:199], v[96:99]
	v_mfma_f32_16x16x32_bf16 v[84:87], v[170:173], v[204:207], v[84:87]
	v_mfma_f32_16x16x32_bf16 v[80:83], v[178:181], v[204:207], v[80:83]
	v_mfma_f32_16x16x32_bf16 v[68:71], v[170:173], v[212:215], v[68:71]
	v_mfma_f32_16x16x32_bf16 v[64:67], v[178:181], v[212:215], v[64:67]
	s_setprio 0
	s_barrier
	s_add_i32 s26, s66, s36
	v_lshl_add_u64 v[216:217], s[78:79], 0, v[130:131]
	s_mov_b32 m0, s26
	ds_read_b128 v[182:185], v149 offset:16384
	ds_read_b128 v[186:189], v149 offset:17408
	ds_read_b128 v[190:193], v149 offset:18432
	ds_read_b128 v[196:199], v149 offset:19456
	ds_read_b128 v[200:203], v149 offset:20480
	ds_read_b128 v[204:207], v149 offset:21504
	ds_read_b128 v[208:211], v149 offset:22528
	ds_read_b128 v[212:215], v149 offset:23552
	s_add_i32 m0, s26, 0x2000
	v_lshl_add_u64 v[218:219], s[78:79], 0, v[134:135]
	s_add_u32 s78, s78, s12
	s_addc_u32 s79, s79, s13
	s_add_i32 s26, s67, s36
	v_lshl_add_u64 v[220:221], s[78:79], 0, v[130:131]
	s_mov_b32 m0, s26
	v_lshl_add_u64 v[222:223], s[78:79], 0, v[134:135]
	s_add_i32 m0, s26, 0x2000
	v_lshl_add_u64 v[224:225], s[56:57], 0, v[128:129]
	s_mov_b32 m0, s37
	v_lshl_add_u64 v[226:227], s[56:57], 0, v[132:133]
	s_mov_b32 m0, s58
	s_nop 0
	s_waitcnt vmcnt(2)
	s_waitcnt lgkmcnt(0)
	s_barrier
	s_setprio 1
	s_waitcnt lgkmcnt(0)
	v_mfma_f32_16x16x32_bf16 v[60:63], v[150:153], v[182:185], v[60:63]
	v_mfma_f32_16x16x32_bf16 v[56:59], v[158:161], v[182:185], v[56:59]
	v_mfma_f32_16x16x32_bf16 v[44:47], v[150:153], v[190:193], v[44:47]
	v_mfma_f32_16x16x32_bf16 v[40:43], v[158:161], v[190:193], v[40:43]
	v_mfma_f32_16x16x32_bf16 v[28:31], v[150:153], v[200:203], v[28:31]
	v_mfma_f32_16x16x32_bf16 v[24:27], v[158:161], v[200:203], v[24:27]
	v_mfma_f32_16x16x32_bf16 v[12:15], v[150:153], v[208:211], v[12:15]
	v_mfma_f32_16x16x32_bf16 v[8:11], v[158:161], v[208:211], v[8:11]
	v_mfma_f32_16x16x32_bf16 v[60:63], v[154:157], v[186:189], v[60:63]
	v_mfma_f32_16x16x32_bf16 v[56:59], v[162:165], v[186:189], v[56:59]
	v_mfma_f32_16x16x32_bf16 v[44:47], v[154:157], v[196:199], v[44:47]
	v_mfma_f32_16x16x32_bf16 v[40:43], v[162:165], v[196:199], v[40:43]
	v_mfma_f32_16x16x32_bf16 v[28:31], v[154:157], v[204:207], v[28:31]
	v_mfma_f32_16x16x32_bf16 v[24:27], v[162:165], v[204:207], v[24:27]
	v_mfma_f32_16x16x32_bf16 v[12:15], v[154:157], v[212:215], v[12:15]
	v_mfma_f32_16x16x32_bf16 v[8:11], v[162:165], v[212:215], v[8:11]
	s_setprio 0
	s_setprio 1
	v_mfma_f32_16x16x32_bf16 v[52:55], v[166:169], v[182:185], v[52:55]
	v_mfma_f32_16x16x32_bf16 v[48:51], v[174:177], v[182:185], v[48:51]
	v_mfma_f32_16x16x32_bf16 v[36:39], v[166:169], v[190:193], v[36:39]
	v_mfma_f32_16x16x32_bf16 v[32:35], v[174:177], v[190:193], v[32:35]
	v_mfma_f32_16x16x32_bf16 v[20:23], v[166:169], v[200:203], v[20:23]
	v_mfma_f32_16x16x32_bf16 v[16:19], v[174:177], v[200:203], v[16:19]
	v_mfma_f32_16x16x32_bf16 v[4:7], v[166:169], v[208:211], v[4:7]
	v_mfma_f32_16x16x32_bf16 v[0:3], v[174:177], v[208:211], v[0:3]
	v_mfma_f32_16x16x32_bf16 v[52:55], v[170:173], v[186:189], v[52:55]
	v_mfma_f32_16x16x32_bf16 v[48:51], v[178:181], v[186:189], v[48:51]
	v_mfma_f32_16x16x32_bf16 v[36:39], v[170:173], v[196:199], v[36:39]
	v_mfma_f32_16x16x32_bf16 v[32:35], v[178:181], v[196:199], v[32:35]
	v_mfma_f32_16x16x32_bf16 v[20:23], v[170:173], v[204:207], v[20:23]
	v_mfma_f32_16x16x32_bf16 v[16:19], v[178:181], v[204:207], v[16:19]
	v_mfma_f32_16x16x32_bf16 v[4:7], v[170:173], v[212:215], v[4:7]
	v_mfma_f32_16x16x32_bf16 v[0:3], v[178:181], v[212:215], v[0:3]
	s_setprio 0
	s_barrier
; #define PG8_STAGE(bufoff, gbase, voff) do { _Pragma("unroll") for (int _i = 0; _i < 2; ++_i) \
;         __builtin_amdgcn_global_load_lds((const unsigned*)((const char*)(gbase) + (voff)[_i]), (PG8_LAS unsigned*)(lds + (bufoff) + ldsw + _i * 8192), 16, 0, 0); } while (0)
; #define PG8_LDA(dst, b, h) do { _Pragma("unroll") for (int m = 0; m < 4; ++m) _Pragma("unroll") for (int k = 0; k < 2; ++k) dst[m][k] = *(const PG8_LAS bf16x8*)(lds + PG8_SA(b, h) + aoff + m * 2048 + k * 1024); } while (0)
; #define PG8_LDB(dst, b, h) do { _Pragma("unroll") for (int n = 0; n < 2; ++n) _Pragma("unroll") for (int k = 0; k < 2; ++k) dst[n][k] = *(const PG8_LAS bf16x8*)(lds + PG8_SB(b, h) + boff + n * 2048 + k * 1024); } while (0)
; #define PG8_WAIT_V(n) asm volatile("s_waitcnt vmcnt(" #n ")" ::: "memory")
; #define PG8_WAIT_L(n) asm volatile("s_waitcnt lgkmcnt(" #n ")" ::: "memory")
; #define PG8_BAR __builtin_amdgcn_s_barrier()
; #define PG8_SCHED __builtin_amdgcn_sched_barrier(0)
; template <class Epi, class Sched, bool ALIGN_EPI = false, bool SP2 = false>
; __device__ __forceinline__ void gemm_phase(PG8_LAS unsigned char* lds, const Gemm g, const Sched& S, const Epi& E) {
;     ...
;             PG8_LDB(B0, 0, 0); PG8_LDB(B1, 0, 1); PG8_SCHED; PG8_LDA(At, 0, 0); PG8_STAGE(PG8_SA(1, 1), a1 + hstep, voffA);
;             PG8_WAIT_V(8); PG8_WAIT_L(0); PG8_BAR; PG8_MMA(0, 0, At, B0); PG8_MMA(0, 1, At, B1); PG8_BAR; PG8_SCHED;
;             PG8_LDA(At, 0, 1); PG8_STAGE(PG8_SB(0, 0), b2, voffB); PG8_STAGE(PG8_SB(0, 1), b2 + hstep, voffB); PG8_STAGE(PG8_SA(0, 0), a2, voffA);
;             PG8_WAIT_V(8); PG8_WAIT_L(0); PG8_BAR; PG8_MMA(1, 0, At, B0); PG8_MMA(1, 1, At, B1); PG8_BAR; PG8_SCHED;
;             PG8_LDB(B0, 1, 0); PG8_LDB(B1, 1, 1); PG8_SCHED; PG8_LDA(At, 1, 0); PG8_STAGE(PG8_SA(0, 1), a2 + hstep, voffA);
;             PG8_WAIT_V(8); PG8_WAIT_L(0); PG8_BAR; PG8_MMA(0, 0, At, B0); PG8_MMA(0, 1, At, B1); PG8_BAR; PG8_SCHED;
;             PG8_LDA(At, 1, 1); PG8_STAGE(PG8_SB(1, 0), b3, voffB); PG8_STAGE(PG8_SB(1, 1), b3 + hstep, voffB); PG8_STAGE(PG8_SA(1, 0), a3, voffA);
;             PG8_WAIT_V(8); PG8_WAIT_L(0); PG8_BAR; PG8_MMA(1, 0, At, B0); PG8_MMA(1, 1, At, B1); PG8_BAR; PG8_SCHED;
	s_add_i32 s26, 0, 0x18000
	s_add_i32 s27, 0, 0x1c000
	v_add_u32_e32 v162, s26, v145
	v_add_u32_e32 v178, s27, v145
	ds_read_b128 v[150:153], v162
	ds_read_b128 v[154:157], v162 offset:1024
	ds_read_b128 v[158:161], v162 offset:2048
	ds_read_b128 v[162:165], v162 offset:3072
	ds_read_b128 v[166:169], v178
	ds_read_b128 v[170:173], v178 offset:1024
	ds_read_b128 v[174:177], v178 offset:2048
	ds_read_b128 v[178:181], v178 offset:3072
	s_add_u32 s56, s56, s12
	s_addc_u32 s57, s57, s13
	s_mov_b32 m0, s59
	v_lshl_add_u64 v[228:229], s[56:57], 0, v[128:129]
	ds_read_b128 v[182:185], v149 offset:32768
	ds_read_b128 v[186:189], v149 offset:33792
	ds_read_b128 v[190:193], v149 offset:34816
	ds_read_b128 v[196:199], v149 offset:35840
	ds_read_b128 v[200:203], v149 offset:36864
	ds_read_b128 v[204:207], v149 offset:37888
	ds_read_b128 v[208:211], v149 offset:38912
	ds_read_b128 v[212:215], v149 offset:39936
	v_lshl_add_u64 v[228:229], s[56:57], 0, v[132:133]
	s_mov_b32 m0, s60
	s_nop 0
	s_waitcnt vmcnt(0)
	s_waitcnt lgkmcnt(0)
	s_barrier
	s_setprio 1
	s_waitcnt lgkmcnt(0)
	v_mfma_f32_16x16x32_bf16 v[120:123], v[150:153], v[182:185], v[120:123]
	v_mfma_f32_16x16x32_bf16 v[124:127], v[158:161], v[182:185], v[124:127]
	v_mfma_f32_16x16x32_bf16 v[108:111], v[150:153], v[190:193], v[108:111]
	v_mfma_f32_16x16x32_bf16 v[104:107], v[158:161], v[190:193], v[104:107]
	v_mfma_f32_16x16x32_bf16 v[92:95], v[150:153], v[200:203], v[92:95]
	v_mfma_f32_16x16x32_bf16 v[88:91], v[158:161], v[200:203], v[88:91]
	v_mfma_f32_16x16x32_bf16 v[76:79], v[150:153], v[208:211], v[76:79]
	v_mfma_f32_16x16x32_bf16 v[72:75], v[158:161], v[208:211], v[72:75]
	v_mfma_f32_16x16x32_bf16 v[120:123], v[154:157], v[186:189], v[120:123]
	v_mfma_f32_16x16x32_bf16 v[124:127], v[162:165], v[186:189], v[124:127]
	v_mfma_f32_16x16x32_bf16 v[108:111], v[154:157], v[196:199], v[108:111]
	v_mfma_f32_16x16x32_bf16 v[104:107], v[162:165], v[196:199], v[104:107]
	v_mfma_f32_16x16x32_bf16 v[92:95], v[154:157], v[204:207], v[92:95]
	v_mfma_f32_16x16x32_bf16 v[88:91], v[162:165], v[204:207], v[88:91]
	v_mfma_f32_16x16x32_bf16 v[76:79], v[154:157], v[212:215], v[76:79]
	v_mfma_f32_16x16x32_bf16 v[72:75], v[162:165], v[212:215], v[72:75]
	s_setprio 0
	s_setprio 1
	v_mfma_f32_16x16x32_bf16 v[116:119], v[166:169], v[182:185], v[116:119]
	v_mfma_f32_16x16x32_bf16 v[112:115], v[174:177], v[182:185], v[112:115]
	v_mfma_f32_16x16x32_bf16 v[100:103], v[166:169], v[190:193], v[100:103]
	v_mfma_f32_16x16x32_bf16 v[96:99], v[174:177], v[190:193], v[96:99]
	v_mfma_f32_16x16x32_bf16 v[84:87], v[166:169], v[200:203], v[84:87]
	v_mfma_f32_16x16x32_bf16 v[80:83], v[174:177], v[200:203], v[80:83]
	v_mfma_f32_16x16x32_bf16 v[68:71], v[166:169], v[208:211], v[68:71]
	v_mfma_f32_16x16x32_bf16 v[64:67], v[174:177], v[208:211], v[64:67]
	v_mfma_f32_16x16x32_bf16 v[116:119], v[170:173], v[186:189], v[116:119]
	v_mfma_f32_16x16x32_bf16 v[112:115], v[178:181], v[186:189], v[112:115]
	v_mfma_f32_16x16x32_bf16 v[100:103], v[170:173], v[196:199], v[100:103]
	v_mfma_f32_16x16x32_bf16 v[96:99], v[178:181], v[196:199], v[96:99]
	v_mfma_f32_16x16x32_bf16 v[84:87], v[170:173], v[204:207], v[84:87]
	v_mfma_f32_16x16x32_bf16 v[80:83], v[178:181], v[204:207], v[80:83]
	v_mfma_f32_16x16x32_bf16 v[68:71], v[170:173], v[212:215], v[68:71]
	v_mfma_f32_16x16x32_bf16 v[64:67], v[178:181], v[212:215], v[64:67]
	s_setprio 0
	s_barrier
	s_add_i32 s26, s26, s36
	v_lshl_add_u64 v[216:217], v[216:217], 0, s[38:39]
	s_mov_b32 m0, s26
	ds_read_b128 v[182:185], v149 offset:49152
	ds_read_b128 v[186:189], v149 offset:50176
	ds_read_b128 v[190:193], v149 offset:51200
	ds_read_b128 v[196:199], v149 offset:52224
	ds_read_b128 v[200:203], v149 offset:53248
	ds_read_b128 v[204:207], v149 offset:54272
	ds_read_b128 v[208:211], v149 offset:55296
	ds_read_b128 v[212:215], v149 offset:56320
	v_lshl_add_u64 v[216:217], v[218:219], 0, s[38:39]
	s_add_i32 m0, s26, 0x2000
	s_add_i32 s26, s27, s36
	v_lshl_add_u64 v[216:217], v[220:221], 0, s[38:39]
	s_mov_b32 m0, s26
	s_nop 0
	v_lshl_add_u64 v[216:217], v[222:223], 0, s[38:39]
	s_add_i32 m0, s26, 0x2000
	s_nop 0
	v_lshl_add_u64 v[216:217], v[224:225], 0, s[38:39]
	s_mov_b32 m0, s62
	s_nop 0
	v_lshl_add_u64 v[216:217], v[226:227], 0, s[38:39]
	s_mov_b32 m0, s63
	s_nop 0
	s_waitcnt vmcnt(0)
	s_waitcnt lgkmcnt(0)
	s_barrier
	s_setprio 1
	s_waitcnt lgkmcnt(0)
	v_mfma_f32_16x16x32_bf16 v[60:63], v[150:153], v[182:185], v[60:63]
	v_mfma_f32_16x16x32_bf16 v[56:59], v[158:161], v[182:185], v[56:59]
	v_mfma_f32_16x16x32_bf16 v[44:47], v[150:153], v[190:193], v[44:47]
	v_mfma_f32_16x16x32_bf16 v[40:43], v[158:161], v[190:193], v[40:43]
	v_mfma_f32_16x16x32_bf16 v[28:31], v[150:153], v[200:203], v[28:31]
	v_mfma_f32_16x16x32_bf16 v[24:27], v[158:161], v[200:203], v[24:27]
	v_mfma_f32_16x16x32_bf16 v[12:15], v[150:153], v[208:211], v[12:15]
	v_mfma_f32_16x16x32_bf16 v[8:11], v[158:161], v[208:211], v[8:11]
	v_mfma_f32_16x16x32_bf16 v[60:63], v[154:157], v[186:189], v[60:63]
	v_mfma_f32_16x16x32_bf16 v[56:59], v[162:165], v[186:189], v[56:59]
	v_mfma_f32_16x16x32_bf16 v[44:47], v[154:157], v[196:199], v[44:47]
	v_mfma_f32_16x16x32_bf16 v[40:43], v[162:165], v[196:199], v[40:43]
	v_mfma_f32_16x16x32_bf16 v[28:31], v[154:157], v[204:207], v[28:31]
	v_mfma_f32_16x16x32_bf16 v[24:27], v[162:165], v[204:207], v[24:27]
	v_mfma_f32_16x16x32_bf16 v[12:15], v[154:157], v[212:215], v[12:15]
	v_mfma_f32_16x16x32_bf16 v[8:11], v[162:165], v[212:215], v[8:11]
	s_setprio 0
	s_setprio 1
	v_mfma_f32_16x16x32_bf16 v[52:55], v[166:169], v[182:185], v[52:55]
	v_mfma_f32_16x16x32_bf16 v[48:51], v[174:177], v[182:185], v[48:51]
	v_mfma_f32_16x16x32_bf16 v[36:39], v[166:169], v[190:193], v[36:39]
	v_mfma_f32_16x16x32_bf16 v[32:35], v[174:177], v[190:193], v[32:35]
	v_mfma_f32_16x16x32_bf16 v[20:23], v[166:169], v[200:203], v[20:23]
	v_mfma_f32_16x16x32_bf16 v[16:19], v[174:177], v[200:203], v[16:19]
	v_mfma_f32_16x16x32_bf16 v[4:7], v[166:169], v[208:211], v[4:7]
	v_mfma_f32_16x16x32_bf16 v[0:3], v[174:177], v[208:211], v[0:3]
	v_mfma_f32_16x16x32_bf16 v[52:55], v[170:173], v[186:189], v[52:55]
	v_mfma_f32_16x16x32_bf16 v[48:51], v[178:181], v[186:189], v[48:51]
	v_mfma_f32_16x16x32_bf16 v[36:39], v[170:173], v[196:199], v[36:39]
	v_mfma_f32_16x16x32_bf16 v[32:35], v[178:181], v[196:199], v[32:35]
	v_mfma_f32_16x16x32_bf16 v[20:23], v[170:173], v[204:207], v[20:23]
	v_mfma_f32_16x16x32_bf16 v[16:19], v[178:181], v[204:207], v[16:19]
	v_mfma_f32_16x16x32_bf16 v[4:7], v[170:173], v[212:215], v[4:7]
	v_mfma_f32_16x16x32_bf16 v[0:3], v[178:181], v[212:215], v[0:3]
	s_setprio 0
	s_barrier
	s_add_u32 s54, s54, 0x100
	s_addc_u32 s55, s55, 0
	s_add_u32 s75, s75, 0x100
	s_addc_u32 s76, s76, 0
	s_cmp_ge_i32 s77, s64
	s_mov_b32 s56, s77
	s_cbranch_scc0 .LBB0_439

; #define PG8_STAGE(bufoff, gbase, voff) do { _Pragma("unroll") for (int _i = 0; _i < 2; ++_i) \
;         __builtin_amdgcn_global_load_lds((const unsigned*)((const char*)(gbase) + (voff)[_i]), (PG8_LAS unsigned*)(lds + (bufoff) + ldsw + _i * 8192), 16, 0, 0); } while (0)
; #define PG8_LDA(dst, b, h) do { _Pragma("unroll") for (int m = 0; m < 4; ++m) _Pragma("unroll") for (int k = 0; k < 2; ++k) dst[m][k] = *(const PG8_LAS bf16x8*)(lds + PG8_SA(b, h) + aoff + m * 2048 + k * 1024); } while (0)
; #define PG8_LDB(dst, b, h) do { _Pragma("unroll") for (int n = 0; n < 2; ++n) _Pragma("unroll") for (int k = 0; k < 2; ++k) dst[n][k] = *(const PG8_LAS bf16x8*)(lds + PG8_SB(b, h) + boff + n * 2048 + k * 1024); } while (0)
; #define PG8_WAIT_V(n) asm volatile("s_waitcnt vmcnt(" #n ")" ::: "memory")
; #define PG8_WAIT_L(n) asm volatile("s_waitcnt lgkmcnt(" #n ")" ::: "memory")
; #define PG8_BAR __builtin_amdgcn_s_barrier()
; #define PG8_SCHED __builtin_amdgcn_sched_barrier(0)
; template <class Epi, class Sched, bool ALIGN_EPI = false, bool SP2 = false>
; __device__ __forceinline__ void gemm_phase(PG8_LAS unsigned char* lds, const Gemm g, const Sched& S, const Epi& E) {
;     ...
;             PG8_LDB(B0, 0, 0); PG8_LDB(B1, 0, 1); PG8_SCHED; PG8_LDA(At, 0, 0); PG8_STAGE(PG8_SA(1, 1), a1 + hstep, voffA);
;             PG8_WAIT_V(8); PG8_WAIT_L(0); PG8_BAR; PG8_MMA(0, 0, At, B0); PG8_MMA(0, 1, At, B1); PG8_BAR; PG8_SCHED;
;             PG8_LDA(At, 0, 1); PG8_STAGE(PG8_SB(0, 0), b2, voffB); PG8_STAGE(PG8_SB(0, 1), b2 + hstep, voffB); PG8_STAGE(PG8_SA(0, 0), a2, voffA);
;             PG8_WAIT_V(8); PG8_WAIT_L(0); PG8_BAR; PG8_MMA(1, 0, At, B0); PG8_MMA(1, 1, At, B1); PG8_BAR; PG8_SCHED;
;             PG8_LDB(B0, 1, 0); PG8_LDB(B1, 1, 1); PG8_SCHED; PG8_LDA(At, 1, 0); PG8_STAGE(PG8_SA(0, 1), a2 + hstep, voffA);
;             PG8_WAIT_V(8); PG8_WAIT_L(0); PG8_BAR; PG8_MMA(0, 0, At, B0); PG8_MMA(0, 1, At, B1); PG8_BAR; PG8_SCHED;
;             PG8_LDA(At, 1, 1); PG8_STAGE(PG8_SB(1, 0), b3, voffB); PG8_STAGE(PG8_SB(1, 1), b3 + hstep, voffB); PG8_STAGE(PG8_SA(1, 0), a3, voffA);
;             PG8_WAIT_V(8); PG8_WAIT_L(0); PG8_BAR; PG8_MMA(1, 0, At, B0); PG8_MMA(1, 1, At, B1); PG8_BAR; PG8_SCHED;
.LBB0_468:
	ds_read_b128 v[150:153], v147
	ds_read_b128 v[154:157], v147 offset:1024
	ds_read_b128 v[158:161], v147 offset:2048
	ds_read_b128 v[162:165], v147 offset:3072
	ds_read_b128 v[166:169], v148
	ds_read_b128 v[170:173], v148 offset:1024
	ds_read_b128 v[174:177], v148 offset:2048
	ds_read_b128 v[178:181], v148 offset:3072
	s_add_i32 s76, s54, 2
	s_add_u32 s26, s52, 0x80
	s_addc_u32 s27, s53, 0
	s_cmp_eq_u32 s64, s54
	s_cselect_b32 s54, s8, s26
	s_cselect_b32 s55, s9, s27
	s_cselect_b32 s79, s51, s75
	s_cselect_b32 s78, s50, s74
	v_lshl_add_u64 v[216:217], s[52:53], 0, v[136:137]
	s_add_i32 m0, s56, 0xc000
	ds_read_b128 v[182:185], v149
	ds_read_b128 v[186:189], v149 offset:1024
	ds_read_b128 v[190:193], v149 offset:2048
	ds_read_b128 v[196:199], v149 offset:3072
	ds_read_b128 v[200:203], v149 offset:4096
	ds_read_b128 v[204:207], v149 offset:5120
	ds_read_b128 v[208:211], v149 offset:6144
	ds_read_b128 v[212:215], v149 offset:7168
	global_load_lds_dwordx4 v[216:217], off
	v_lshl_add_u64 v[216:217], s[52:53], 0, v[138:139]
	s_add_i32 m0, s56, 0xe000
	s_nop 0
	global_load_lds_dwordx4 v[216:217], off
	s_waitcnt vmcnt(8)
	s_waitcnt lgkmcnt(0)
	s_barrier
	s_setprio 1
	s_waitcnt lgkmcnt(0)
	v_mfma_f32_16x16x32_bf16 v[120:123], v[150:153], v[182:185], v[120:123]
	v_mfma_f32_16x16x32_bf16 v[124:127], v[158:161], v[182:185], v[124:127]
	v_mfma_f32_16x16x32_bf16 v[108:111], v[150:153], v[190:193], v[108:111]
	v_mfma_f32_16x16x32_bf16 v[104:107], v[158:161], v[190:193], v[104:107]
	v_mfma_f32_16x16x32_bf16 v[92:95], v[150:153], v[200:203], v[92:95]
	v_mfma_f32_16x16x32_bf16 v[88:91], v[158:161], v[200:203], v[88:91]
	v_mfma_f32_16x16x32_bf16 v[76:79], v[150:153], v[208:211], v[76:79]
	v_mfma_f32_16x16x32_bf16 v[72:75], v[158:161], v[208:211], v[72:75]
	v_mfma_f32_16x16x32_bf16 v[120:123], v[154:157], v[186:189], v[120:123]
	v_mfma_f32_16x16x32_bf16 v[124:127], v[162:165], v[186:189], v[124:127]
	v_mfma_f32_16x16x32_bf16 v[108:111], v[154:157], v[196:199], v[108:111]
	v_mfma_f32_16x16x32_bf16 v[104:107], v[162:165], v[196:199], v[104:107]
	v_mfma_f32_16x16x32_bf16 v[92:95], v[154:157], v[204:207], v[92:95]
	v_mfma_f32_16x16x32_bf16 v[88:91], v[162:165], v[204:207], v[88:91]
	v_mfma_f32_16x16x32_bf16 v[76:79], v[154:157], v[212:215], v[76:79]
	v_mfma_f32_16x16x32_bf16 v[72:75], v[162:165], v[212:215], v[72:75]
	s_setprio 0
	s_setprio 1
	v_mfma_f32_16x16x32_bf16 v[116:119], v[166:169], v[182:185], v[116:119]
	v_mfma_f32_16x16x32_bf16 v[112:115], v[174:177], v[182:185], v[112:115]
	v_mfma_f32_16x16x32_bf16 v[100:103], v[166:169], v[190:193], v[100:103]
	v_mfma_f32_16x16x32_bf16 v[96:99], v[174:177], v[190:193], v[96:99]
	v_mfma_f32_16x16x32_bf16 v[84:87], v[166:169], v[200:203], v[84:87]
	v_mfma_f32_16x16x32_bf16 v[80:83], v[174:177], v[200:203], v[80:83]
	v_mfma_f32_16x16x32_bf16 v[68:71], v[166:169], v[208:211], v[68:71]
	v_mfma_f32_16x16x32_bf16 v[64:67], v[174:177], v[208:211], v[64:67]
	v_mfma_f32_16x16x32_bf16 v[116:119], v[170:173], v[186:189], v[116:119]
	v_mfma_f32_16x16x32_bf16 v[112:115], v[178:181], v[186:189], v[112:115]
	v_mfma_f32_16x16x32_bf16 v[100:103], v[170:173], v[196:199], v[100:103]
	v_mfma_f32_16x16x32_bf16 v[96:99], v[178:181], v[196:199], v[96:99]
	v_mfma_f32_16x16x32_bf16 v[84:87], v[170:173], v[204:207], v[84:87]
	v_mfma_f32_16x16x32_bf16 v[80:83], v[178:181], v[204:207], v[80:83]
	v_mfma_f32_16x16x32_bf16 v[68:71], v[170:173], v[212:215], v[68:71]
	v_mfma_f32_16x16x32_bf16 v[64:67], v[178:181], v[212:215], v[64:67]
	s_setprio 0
	s_barrier
	s_add_i32 s26, s65, s37
	v_lshl_add_u64 v[216:217], s[78:79], 0, v[130:131]
	s_mov_b32 m0, s26
	ds_read_b128 v[182:185], v149 offset:16384
	ds_read_b128 v[186:189], v149 offset:17408
	ds_read_b128 v[190:193], v149 offset:18432
	ds_read_b128 v[196:199], v149 offset:19456
	ds_read_b128 v[200:203], v149 offset:20480
	ds_read_b128 v[204:207], v149 offset:21504
	ds_read_b128 v[208:211], v149 offset:22528
	ds_read_b128 v[212:215], v149 offset:23552
	s_add_i32 m0, s26, 0x2000
	v_lshl_add_u64 v[218:219], s[78:79], 0, v[134:135]
	s_add_u32 s78, s78, s10
	s_addc_u32 s79, s79, s11
	s_add_i32 s26, s66, s37
	v_lshl_add_u64 v[220:221], s[78:79], 0, v[130:131]
	s_mov_b32 m0, s26
	v_lshl_add_u64 v[222:223], s[78:79], 0, v[134:135]
	s_add_i32 m0, s26, 0x2000
	v_lshl_add_u64 v[224:225], s[54:55], 0, v[128:129]
	s_mov_b32 m0, s56
	v_lshl_add_u64 v[226:227], s[54:55], 0, v[132:133]
	s_mov_b32 m0, s57
	s_nop 0
	s_waitcnt vmcnt(2)
	s_waitcnt lgkmcnt(0)
	s_barrier
	s_setprio 1
	s_waitcnt lgkmcnt(0)
	v_mfma_f32_16x16x32_bf16 v[60:63], v[150:153], v[182:185], v[60:63]
	v_mfma_f32_16x16x32_bf16 v[56:59], v[158:161], v[182:185], v[56:59]
	v_mfma_f32_16x16x32_bf16 v[44:47], v[150:153], v[190:193], v[44:47]
	v_mfma_f32_16x16x32_bf16 v[40:43], v[158:161], v[190:193], v[40:43]
	v_mfma_f32_16x16x32_bf16 v[28:31], v[150:153], v[200:203], v[28:31]
	v_mfma_f32_16x16x32_bf16 v[24:27], v[158:161], v[200:203], v[24:27]
	v_mfma_f32_16x16x32_bf16 v[12:15], v[150:153], v[208:211], v[12:15]
	v_mfma_f32_16x16x32_bf16 v[8:11], v[158:161], v[208:211], v[8:11]
	v_mfma_f32_16x16x32_bf16 v[60:63], v[154:157], v[186:189], v[60:63]
	v_mfma_f32_16x16x32_bf16 v[56:59], v[162:165], v[186:189], v[56:59]
	v_mfma_f32_16x16x32_bf16 v[44:47], v[154:157], v[196:199], v[44:47]
	v_mfma_f32_16x16x32_bf16 v[40:43], v[162:165], v[196:199], v[40:43]
	v_mfma_f32_16x16x32_bf16 v[28:31], v[154:157], v[204:207], v[28:31]
	v_mfma_f32_16x16x32_bf16 v[24:27], v[162:165], v[204:207], v[24:27]
	v_mfma_f32_16x16x32_bf16 v[12:15], v[154:157], v[212:215], v[12:15]
	v_mfma_f32_16x16x32_bf16 v[8:11], v[162:165], v[212:215], v[8:11]
	s_setprio 0
	s_setprio 1
	v_mfma_f32_16x16x32_bf16 v[52:55], v[166:169], v[182:185], v[52:55]
	v_mfma_f32_16x16x32_bf16 v[48:51], v[174:177], v[182:185], v[48:51]
	v_mfma_f32_16x16x32_bf16 v[36:39], v[166:169], v[190:193], v[36:39]
	v_mfma_f32_16x16x32_bf16 v[32:35], v[174:177], v[190:193], v[32:35]
	v_mfma_f32_16x16x32_bf16 v[20:23], v[166:169], v[200:203], v[20:23]
	v_mfma_f32_16x16x32_bf16 v[16:19], v[174:177], v[200:203], v[16:19]
	v_mfma_f32_16x16x32_bf16 v[4:7], v[166:169], v[208:211], v[4:7]
	v_mfma_f32_16x16x32_bf16 v[0:3], v[174:177], v[208:211], v[0:3]
	v_mfma_f32_16x16x32_bf16 v[52:55], v[170:173], v[186:189], v[52:55]
	v_mfma_f32_16x16x32_bf16 v[48:51], v[178:181], v[186:189], v[48:51]
	v_mfma_f32_16x16x32_bf16 v[36:39], v[170:173], v[196:199], v[36:39]
	v_mfma_f32_16x16x32_bf16 v[32:35], v[178:181], v[196:199], v[32:35]
	v_mfma_f32_16x16x32_bf16 v[20:23], v[170:173], v[204:207], v[20:23]
	v_mfma_f32_16x16x32_bf16 v[16:19], v[178:181], v[204:207], v[16:19]
	v_mfma_f32_16x16x32_bf16 v[4:7], v[170:173], v[212:215], v[4:7]
	v_mfma_f32_16x16x32_bf16 v[0:3], v[178:181], v[212:215], v[0:3]
	s_setprio 0
	s_barrier
; #define PG8_STAGE(bufoff, gbase, voff) do { _Pragma("unroll") for (int _i = 0; _i < 2; ++_i) \
;         __builtin_amdgcn_global_load_lds((const unsigned*)((const char*)(gbase) + (voff)[_i]), (PG8_LAS unsigned*)(lds + (bufoff) + ldsw + _i * 8192), 16, 0, 0); } while (0)
; #define PG8_LDA(dst, b, h) do { _Pragma("unroll") for (int m = 0; m < 4; ++m) _Pragma("unroll") for (int k = 0; k < 2; ++k) dst[m][k] = *(const PG8_LAS bf16x8*)(lds + PG8_SA(b, h) + aoff + m * 2048 + k * 1024); } while (0)
; #define PG8_LDB(dst, b, h) do { _Pragma("unroll") for (int n = 0; n < 2; ++n) _Pragma("unroll") for (int k = 0; k < 2; ++k) dst[n][k] = *(const PG8_LAS bf16x8*)(lds + PG8_SB(b, h) + boff + n * 2048 + k * 1024); } while (0)
; #define PG8_WAIT_V(n) asm volatile("s_waitcnt vmcnt(" #n ")" ::: "memory")
; #define PG8_WAIT_L(n) asm volatile("s_waitcnt lgkmcnt(" #n ")" ::: "memory")
; #define PG8_BAR __builtin_amdgcn_s_barrier()
; #define PG8_SCHED __builtin_amdgcn_sched_barrier(0)
; template <class Epi, class Sched, bool ALIGN_EPI = false, bool SP2 = false>
; __device__ __forceinline__ void gemm_phase(PG8_LAS unsigned char* lds, const Gemm g, const Sched& S, const Epi& E) {
;     ...
;             PG8_LDB(B0, 0, 0); PG8_LDB(B1, 0, 1); PG8_SCHED; PG8_LDA(At, 0, 0); PG8_STAGE(PG8_SA(1, 1), a1 + hstep, voffA);
;             PG8_WAIT_V(8); PG8_WAIT_L(0); PG8_BAR; PG8_MMA(0, 0, At, B0); PG8_MMA(0, 1, At, B1); PG8_BAR; PG8_SCHED;
;             PG8_LDA(At, 0, 1); PG8_STAGE(PG8_SB(0, 0), b2, voffB); PG8_STAGE(PG8_SB(0, 1), b2 + hstep, voffB); PG8_STAGE(PG8_SA(0, 0), a2, voffA);
;             PG8_WAIT_V(8); PG8_WAIT_L(0); PG8_BAR; PG8_MMA(1, 0, At, B0); PG8_MMA(1, 1, At, B1); PG8_BAR; PG8_SCHED;
;             PG8_LDB(B0, 1, 0); PG8_LDB(B1, 1, 1); PG8_SCHED; PG8_LDA(At, 1, 0); PG8_STAGE(PG8_SA(0, 1), a2 + hstep, voffA);
;             PG8_WAIT_V(8); PG8_WAIT_L(0); PG8_BAR; PG8_MMA(0, 0, At, B0); PG8_MMA(0, 1, At, B1); PG8_BAR; PG8_SCHED;
;             PG8_LDA(At, 1, 1); PG8_STAGE(PG8_SB(1, 0), b3, voffB); PG8_STAGE(PG8_SB(1, 1), b3 + hstep, voffB); PG8_STAGE(PG8_SA(1, 0), a3, voffA);
;             PG8_WAIT_V(8); PG8_WAIT_L(0); PG8_BAR; PG8_MMA(1, 0, At, B0); PG8_MMA(1, 1, At, B1); PG8_BAR; PG8_SCHED;
	s_add_i32 s26, 0, 0x18000
	s_add_i32 s27, 0, 0x1c000
	v_add_u32_e32 v162, s26, v145
	v_add_u32_e32 v178, s27, v145
	ds_read_b128 v[150:153], v162
	ds_read_b128 v[154:157], v162 offset:1024
	ds_read_b128 v[158:161], v162 offset:2048
	ds_read_b128 v[162:165], v162 offset:3072
	ds_read_b128 v[166:169], v178
	ds_read_b128 v[170:173], v178 offset:1024
	ds_read_b128 v[174:177], v178 offset:2048
	ds_read_b128 v[178:181], v178 offset:3072
	s_add_u32 s54, s54, s10
	s_addc_u32 s55, s55, s11
	s_mov_b32 m0, s58
	v_lshl_add_u64 v[228:229], s[54:55], 0, v[128:129]
	ds_read_b128 v[182:185], v149 offset:32768
	ds_read_b128 v[186:189], v149 offset:33792
	ds_read_b128 v[190:193], v149 offset:34816
	ds_read_b128 v[196:199], v149 offset:35840
	ds_read_b128 v[200:203], v149 offset:36864
	ds_read_b128 v[204:207], v149 offset:37888
	ds_read_b128 v[208:211], v149 offset:38912
	ds_read_b128 v[212:215], v149 offset:39936
	v_lshl_add_u64 v[228:229], s[54:55], 0, v[132:133]
	s_mov_b32 m0, s59
	s_nop 0
	s_waitcnt vmcnt(0)
	s_waitcnt lgkmcnt(0)
	s_barrier
	s_setprio 1
	s_waitcnt lgkmcnt(0)
	v_mfma_f32_16x16x32_bf16 v[120:123], v[150:153], v[182:185], v[120:123]
	v_mfma_f32_16x16x32_bf16 v[124:127], v[158:161], v[182:185], v[124:127]
	v_mfma_f32_16x16x32_bf16 v[108:111], v[150:153], v[190:193], v[108:111]
	v_mfma_f32_16x16x32_bf16 v[104:107], v[158:161], v[190:193], v[104:107]
	v_mfma_f32_16x16x32_bf16 v[92:95], v[150:153], v[200:203], v[92:95]
	v_mfma_f32_16x16x32_bf16 v[88:91], v[158:161], v[200:203], v[88:91]
	v_mfma_f32_16x16x32_bf16 v[76:79], v[150:153], v[208:211], v[76:79]
	v_mfma_f32_16x16x32_bf16 v[72:75], v[158:161], v[208:211], v[72:75]
	v_mfma_f32_16x16x32_bf16 v[120:123], v[154:157], v[186:189], v[120:123]
	v_mfma_f32_16x16x32_bf16 v[124:127], v[162:165], v[186:189], v[124:127]
	v_mfma_f32_16x16x32_bf16 v[108:111], v[154:157], v[196:199], v[108:111]
	v_mfma_f32_16x16x32_bf16 v[104:107], v[162:165], v[196:199], v[104:107]
	v_mfma_f32_16x16x32_bf16 v[92:95], v[154:157], v[204:207], v[92:95]
	v_mfma_f32_16x16x32_bf16 v[88:91], v[162:165], v[204:207], v[88:91]
	v_mfma_f32_16x16x32_bf16 v[76:79], v[154:157], v[212:215], v[76:79]
	v_mfma_f32_16x16x32_bf16 v[72:75], v[162:165], v[212:215], v[72:75]
	s_setprio 0
	s_setprio 1
	v_mfma_f32_16x16x32_bf16 v[116:119], v[166:169], v[182:185], v[116:119]
	v_mfma_f32_16x16x32_bf16 v[112:115], v[174:177], v[182:185], v[112:115]
	v_mfma_f32_16x16x32_bf16 v[100:103], v[166:169], v[190:193], v[100:103]
	v_mfma_f32_16x16x32_bf16 v[96:99], v[174:177], v[190:193], v[96:99]
	v_mfma_f32_16x16x32_bf16 v[84:87], v[166:169], v[200:203], v[84:87]
	v_mfma_f32_16x16x32_bf16 v[80:83], v[174:177], v[200:203], v[80:83]
	v_mfma_f32_16x16x32_bf16 v[68:71], v[166:169], v[208:211], v[68:71]
	v_mfma_f32_16x16x32_bf16 v[64:67], v[174:177], v[208:211], v[64:67]
	v_mfma_f32_16x16x32_bf16 v[116:119], v[170:173], v[186:189], v[116:119]
	v_mfma_f32_16x16x32_bf16 v[112:115], v[178:181], v[186:189], v[112:115]
	v_mfma_f32_16x16x32_bf16 v[100:103], v[170:173], v[196:199], v[100:103]
	v_mfma_f32_16x16x32_bf16 v[96:99], v[178:181], v[196:199], v[96:99]
	v_mfma_f32_16x16x32_bf16 v[84:87], v[170:173], v[204:207], v[84:87]
	v_mfma_f32_16x16x32_bf16 v[80:83], v[178:181], v[204:207], v[80:83]
	v_mfma_f32_16x16x32_bf16 v[68:71], v[170:173], v[212:215], v[68:71]
	v_mfma_f32_16x16x32_bf16 v[64:67], v[178:181], v[212:215], v[64:67]
	s_setprio 0
	s_barrier
	s_add_i32 s26, s26, s37
	v_lshl_add_u64 v[216:217], v[216:217], 0, s[22:23]
	s_mov_b32 m0, s26
	ds_read_b128 v[182:185], v149 offset:49152
	ds_read_b128 v[186:189], v149 offset:50176
	ds_read_b128 v[190:193], v149 offset:51200
	ds_read_b128 v[196:199], v149 offset:52224
	ds_read_b128 v[200:203], v149 offset:53248
	ds_read_b128 v[204:207], v149 offset:54272
	ds_read_b128 v[208:211], v149 offset:55296
	ds_read_b128 v[212:215], v149 offset:56320
	v_lshl_add_u64 v[216:217], v[218:219], 0, s[22:23]
	s_add_i32 m0, s26, 0x2000
	s_add_i32 s26, s27, s37
	v_lshl_add_u64 v[216:217], v[220:221], 0, s[22:23]
	s_mov_b32 m0, s26
	s_nop 0
	v_lshl_add_u64 v[216:217], v[222:223], 0, s[22:23]
	s_add_i32 m0, s26, 0x2000
	s_nop 0
	v_lshl_add_u64 v[216:217], v[224:225], 0, s[22:23]
	s_mov_b32 m0, s61
	s_nop 0
	v_lshl_add_u64 v[216:217], v[226:227], 0, s[22:23]
	s_mov_b32 m0, s62
	s_nop 0
	s_waitcnt vmcnt(0)
	s_waitcnt lgkmcnt(0)
	s_barrier
	s_setprio 1
	s_waitcnt lgkmcnt(0)
	v_mfma_f32_16x16x32_bf16 v[60:63], v[150:153], v[182:185], v[60:63]
	v_mfma_f32_16x16x32_bf16 v[56:59], v[158:161], v[182:185], v[56:59]
	v_mfma_f32_16x16x32_bf16 v[44:47], v[150:153], v[190:193], v[44:47]
	v_mfma_f32_16x16x32_bf16 v[40:43], v[158:161], v[190:193], v[40:43]
	v_mfma_f32_16x16x32_bf16 v[28:31], v[150:153], v[200:203], v[28:31]
	v_mfma_f32_16x16x32_bf16 v[24:27], v[158:161], v[200:203], v[24:27]
	v_mfma_f32_16x16x32_bf16 v[12:15], v[150:153], v[208:211], v[12:15]
	v_mfma_f32_16x16x32_bf16 v[8:11], v[158:161], v[208:211], v[8:11]
	v_mfma_f32_16x16x32_bf16 v[60:63], v[154:157], v[186:189], v[60:63]
	v_mfma_f32_16x16x32_bf16 v[56:59], v[162:165], v[186:189], v[56:59]
	v_mfma_f32_16x16x32_bf16 v[44:47], v[154:157], v[196:199], v[44:47]
	v_mfma_f32_16x16x32_bf16 v[40:43], v[162:165], v[196:199], v[40:43]
	v_mfma_f32_16x16x32_bf16 v[28:31], v[154:157], v[204:207], v[28:31]
	v_mfma_f32_16x16x32_bf16 v[24:27], v[162:165], v[204:207], v[24:27]
	v_mfma_f32_16x16x32_bf16 v[12:15], v[154:157], v[212:215], v[12:15]
	v_mfma_f32_16x16x32_bf16 v[8:11], v[162:165], v[212:215], v[8:11]
	s_setprio 0
	s_setprio 1
	v_mfma_f32_16x16x32_bf16 v[52:55], v[166:169], v[182:185], v[52:55]
	v_mfma_f32_16x16x32_bf16 v[48:51], v[174:177], v[182:185], v[48:51]
	v_mfma_f32_16x16x32_bf16 v[36:39], v[166:169], v[190:193], v[36:39]
	v_mfma_f32_16x16x32_bf16 v[32:35], v[174:177], v[190:193], v[32:35]
	v_mfma_f32_16x16x32_bf16 v[20:23], v[166:169], v[200:203], v[20:23]
	v_mfma_f32_16x16x32_bf16 v[16:19], v[174:177], v[200:203], v[16:19]
	v_mfma_f32_16x16x32_bf16 v[4:7], v[166:169], v[208:211], v[4:7]
	v_mfma_f32_16x16x32_bf16 v[0:3], v[174:177], v[208:211], v[0:3]
	v_mfma_f32_16x16x32_bf16 v[52:55], v[170:173], v[186:189], v[52:55]
	v_mfma_f32_16x16x32_bf16 v[48:51], v[178:181], v[186:189], v[48:51]
	v_mfma_f32_16x16x32_bf16 v[36:39], v[170:173], v[196:199], v[36:39]
	v_mfma_f32_16x16x32_bf16 v[32:35], v[178:181], v[196:199], v[32:35]
	v_mfma_f32_16x16x32_bf16 v[20:23], v[170:173], v[204:207], v[20:23]
	v_mfma_f32_16x16x32_bf16 v[16:19], v[178:181], v[204:207], v[16:19]
	v_mfma_f32_16x16x32_bf16 v[4:7], v[170:173], v[212:215], v[4:7]
	v_mfma_f32_16x16x32_bf16 v[0:3], v[178:181], v[212:215], v[0:3]
	s_setprio 0
	s_barrier
	s_add_u32 s52, s52, 0x100
	s_addc_u32 s53, s53, 0
	s_add_u32 s74, s74, 0x100
	s_addc_u32 s75, s75, 0
	s_cmp_ge_i32 s76, s63
	s_mov_b32 s54, s76
	s_cbranch_scc0 .LBB0_468
